# v82 + ph_win: WG-to-tile rotation in rounds 4..8 so every WG gets exactly one rope (q/k) tile in the 9 full rounds (256-WG grids only)
# speedup vs baseline: 1.0094x; 1.0008x over previous
;     DI bool next(int i, Unit& u) const {
;         const long L = (long)i * G + c; if (L >= nwg) return false;
;         int wgid = (int)L; { const int q = nwg / NXCD, r = nwg % NXCD, xcd = wgid % NXCD, off = wgid / NXCD; wgid = (xcd < r ? xcd * (q + 1) : r * (q + 1) + (xcd - r) * q) + off; }
;         const int nig = WGM * nN, gid = wgid / nig, fm = gid * WGM, gsz = (nM - fm) < WGM ? (nM - fm) : WGM;
;         u.pm = fm + ((wgid % nig) % gsz); u.pn = (wgid % nig) / gsz; return true;
.LBB0_89:
	s_add_i32 s73, s73, 1
	s_mul_i32 s4, s73, s15
	s_mul_hi_u32 s5, s73, s14
	s_add_i32 s5, s5, s4
	s_mul_i32 s4, s73, s14
	s_add_u32 s56, s4, s12
	s_addc_u32 s57, s5, s72
	v_mov_b32_e32 v2, s99
	v_mov_b32_e32 v3, 0
	v_cmp_lt_i64_e64 s[4:5], s[56:57], v[2:3]
	v_add_u32_e32 v2, -1, v2
	v_cmp_gt_i64_e32 vcc, s[56:57], v[2:3]
	s_cbranch_vccnz .LBB0_91
	s_cmp_eq_u32 s14, 0x100
	s_cbranch_scc0 .Lnorot_win
	s_add_i32 s7, s56, 64
	s_and_b32 s17, s56, 0xffffff00
	s_and_b32 s7, s7, 0xff
	s_or_b32 s7, s7, s17
	s_sub_u32 s17, s56, 0x400
	s_cmp_lt_u32 s17, 0x500
	s_cselect_b32 s56, s7, s56
.Lnorot_win:
	s_ashr_i32 s7, s56, 31
	s_lshr_b32 s7, s7, 29
	s_add_i32 s7, s56, s7
	s_ashr_i32 s17, s7, 3
	s_and_b32 s7, s7, -8
	s_sub_i32 s7, s56, s7
	s_cmp_lt_i32 s7, 0
	s_cselect_b32 s18, s74, 0x130
	s_mul_i32 s7, s18, s7
	s_add_i32 s7, s7, s17
	s_mul_hi_i32 s17, s7, 0x6bca1af3
	s_lshr_b32 s18, s17, 31
	s_ashr_i32 s17, s17, 6
	s_add_i32 s17, s17, s18
	s_lshl_b32 s18, s17, 2
	s_sub_i32 s19, 64, s18
	s_min_i32 s19, s19, 4
	s_abs_i32 s22, s19
	v_cvt_f32_u32_e32 v2, s22
	s_sub_i32 s42, 0, s22
	s_mulk_i32 s17, 0x98
	s_sub_i32 s7, s7, s17
	v_rcp_iflag_f32_e32 v2, v2
	s_abs_i32 s17, s7
	s_xor_b32 s23, s7, s19
	s_ashr_i32 s23, s23, 31
	v_mul_f32_e32 v2, 0x4f7ffffe, v2
	v_cvt_u32_f32_e32 v2, v2
	s_nop 0
	v_readfirstlane_b32 s43, v2
	s_mul_i32 s42, s42, s43
	s_mul_hi_u32 s42, s43, s42
	s_add_i32 s43, s43, s42
	s_mul_hi_u32 s42, s17, s43
	s_mul_i32 s43, s42, s22
	s_sub_i32 s17, s17, s43
	s_add_i32 s52, s42, 1
	s_sub_i32 s43, s17, s22
	s_cmp_ge_u32 s17, s22
	s_cselect_b32 s42, s52, s42
	s_cselect_b32 s17, s43, s17
	s_add_i32 s43, s42, 1
	s_cmp_ge_u32 s17, s22
	s_cselect_b32 s17, s43, s42
	s_xor_b32 s17, s17, s23
	s_sub_i32 s52, s17, s23
	s_mul_i32 s17, s52, s19
	s_sub_i32 s7, s7, s17
	s_add_i32 s54, s7, s18
